# slack-workgroup late start in all four GEMMs (layer 0 of up, out, down), no group stagger
# baseline (speedup 1.0000x reference)
; #define PG8_STAGE(bufoff, gbase, voff) do { _Pragma("unroll") for (int _i = 0; _i < 2; ++_i) \
;         __builtin_amdgcn_global_load_lds((const unsigned*)((const char*)(gbase) + (voff)[_i]), (LAS unsigned*)(lds + (bufoff) + ldsw + _i * 8192), 16, 0, 0); } while (0)
; #define PG8_WAIT_V(n) asm volatile("s_waitcnt vmcnt(" #n ")" ::: "memory")
; #define PG8_BAR __builtin_amdgcn_s_barrier()
; template <class Epi, class Sched>
; __device__ __forceinline__ void gemm_phase(LAS unsigned char* lds, const Gemm g, const Sched& S, const Epi& E) {
;     ...
;     const unsigned ldsw = (unsigned)wid * 1024u;
;     const int aoff = lds_byte(wr * 64 + fr, fq * 8), boff = lds_byte(wc * 32 + fr, fq * 8);
;     ...
;     PG8_STAGE(PG8_SB(0, 0), cB, voffB); PG8_STAGE(PG8_SA(0, 0), cA, voffA); PG8_STAGE(PG8_SB(0, 1), cB + hstep, voffB); PG8_STAGE(PG8_SA(0, 1), cA + hstep, voffA);
;     if (wr == 1) PG8_BAR;
;     PG8_WAIT_V(4); PG8_BAR;
;     PG8_STAGE(PG8_SB(1, 0), cB + kstep, voffB); PG8_STAGE(PG8_SA(1, 0), cA + kstep, voffA); PG8_STAGE(PG8_SB(1, 1), cB + hstep + kstep, voffB);
;     PG8_WAIT_V(6); PG8_BAR;
.LBB0_511:
	v_lshrrev_b32_e32 v18, 1, v6
	v_and_b32_e32 v18, 24, v18
	s_lshl_b32 s13, s13, 5
	v_mov_b32_e32 v145, v8
	v_and_b32_e32 v7, 15, v6
	v_lshlrev_b32_e32 v19, 1, v18
	v_lshlrev_b32_e32 v6, 2, v6
	s_and_b32 s15, s13, 0x60
	v_lshl_add_u64 v[10:11], s[74:75], 0, v[144:145]
	v_mov_b32_e32 v141, v8
	v_lshl_or_b32 v9, s14, 6, v7
	v_lshl_or_b32 v7, v7, 6, v19
	s_lshl_b32 s14, s14, 13
	v_and_b32_e32 v6, 32, v6
	s_lshl_b32 s13, s15, 7
	v_lshl_add_u64 v[12:13], s[74:75], 0, v[140:141]
	v_mov_b32_e32 v147, v8
	v_bitop3_b32 v19, v7, s14, v6 bitop3:0xde
	v_bitop3_b32 v152, v7, s13, v6 bitop3:0xde
	s_add_i32 m0, s1, 0x18000
	v_lshl_add_u64 v[6:7], v[10:11], 0, s[94:95]
	v_lshl_add_u64 v[14:15], s[72:73], 0, v[146:147]
	v_mov_b32_e32 v143, v8
	s_waitcnt vmcnt(4)
	s_barrier
	global_load_lds_dwordx4 v[6:7], off
	v_lshl_add_u64 v[6:7], v[12:13], 0, s[94:95]
	s_add_i32 m0, s1, 0x1a000
	s_add_i32 s13, s1, 0x8000
	s_add_i32 s14, s1, 0xa000
	v_lshl_add_u64 v[16:17], s[72:73], 0, v[142:143]
	global_load_lds_dwordx4 v[6:7], off
	v_lshl_add_u64 v[6:7], v[14:15], 0, s[94:95]
	s_mov_b32 m0, s13
	s_add_u32 s16, s74, 0x40080
	global_load_lds_dwordx4 v[6:7], off
	v_lshl_add_u64 v[6:7], v[16:17], 0, s[94:95]
	s_mov_b32 m0, s14
	s_addc_u32 s17, s75, 0
	global_load_lds_dwordx4 v[6:7], off
	s_add_i32 m0, s1, 0x1c000
	v_lshl_add_u64 v[6:7], s[16:17], 0, v[144:145]
	global_load_lds_dwordx4 v[6:7], off
	v_lshl_add_u64 v[6:7], s[16:17], 0, v[140:141]
	s_add_i32 m0, s1, 0x1e000
	v_or_b32_e32 v153, s15, v18
	global_load_lds_dwordx4 v[6:7], off
	v_lshlrev_b32_e32 v6, 14, v4
	v_and_b32_e32 v6, 0xffff8000, v6
	v_lshl_add_u32 v3, v3, 11, v6
	v_and_b32_e32 v4, 1, v4
	v_lshl_or_b32 v3, v4, 6, v3
	v_lshl_add_u32 v148, v5, 1, v3
	v_lshlrev_b32_e32 v3, 14, v0
	v_and_b32_e32 v3, 0xffff8000, v3
	s_waitcnt vmcnt(6)
	v_lshl_add_u32 v1, v1, 11, v3
	v_and_b32_e32 v0, 1, v0
	v_lshl_or_b32 v0, v0, 6, v1
	v_mov_b32_e32 v149, v8
	v_lshl_add_u32 v150, v2, 1, v0
	v_mov_b32_e32 v151, v8
	s_mov_b32 s15, 0
	v_add_u32_e32 v154, 16, v19
	s_barrier
	s_cmp_lg_u32 s46, 0x100
	s_cbranch_scc1 .Lds512_x
	s_and_b32 s99, s2, 0xff
	s_cmp_eq_u32 s99, 0
	s_cbranch_scc1 .Lds512_x
	s_cmp_lt_u32 s92, s99
	s_cbranch_scc1 .Lds512_x
	s_mov_b32 s98, 9
	s_min_u32 s98, s98, 20
.Lds512_l:
	s_sleep 32
	s_sub_u32 s98, s98, 1
	s_cmp_gt_i32 s98, 0
	s_cbranch_scc1 .Lds512_l

; #define PG8_STAGE(bufoff, gbase, voff) do { _Pragma("unroll") for (int _i = 0; _i < 2; ++_i) \
;         __builtin_amdgcn_global_load_lds((const unsigned*)((const char*)(gbase) + (voff)[_i]), (LAS unsigned*)(lds + (bufoff) + ldsw + _i * 8192), 16, 0, 0); } while (0)
; #define PG8_WAIT_V(n) asm volatile("s_waitcnt vmcnt(" #n ")" ::: "memory")
; #define PG8_BAR __builtin_amdgcn_s_barrier()
; template <class Epi, class Sched>
; __device__ __forceinline__ void gemm_phase(LAS unsigned char* lds, const Gemm g, const Sched& S, const Epi& E) {
;     ...
;     const unsigned ldsw = (unsigned)wid * 1024u;
;     const int aoff = lds_byte(wr * 64 + fr, fq * 8), boff = lds_byte(wc * 32 + fr, fq * 8);
;     ...
;     PG8_STAGE(PG8_SB(0, 0), cB, voffB); PG8_STAGE(PG8_SA(0, 0), cA, voffA); PG8_STAGE(PG8_SB(0, 1), cB + hstep, voffB); PG8_STAGE(PG8_SA(0, 1), cA + hstep, voffA);
;     if (wr == 1) PG8_BAR;
;     PG8_WAIT_V(4); PG8_BAR;
;     PG8_STAGE(PG8_SB(1, 0), cB + kstep, voffB); PG8_STAGE(PG8_SA(1, 0), cA + kstep, voffA); PG8_STAGE(PG8_SB(1, 1), cB + hstep + kstep, voffB);
;     PG8_WAIT_V(6); PG8_BAR;
.LBB0_642:
	v_lshrrev_b32_e32 v18, 1, v6
	v_and_b32_e32 v18, 24, v18
	s_lshl_b32 s1, s1, 5
	v_mov_b32_e32 v145, v8
	v_and_b32_e32 v7, 15, v6
	v_lshlrev_b32_e32 v19, 1, v18
	v_lshlrev_b32_e32 v6, 2, v6
	s_and_b32 s18, s1, 0x60
	v_lshl_add_u64 v[10:11], s[70:71], 0, v[144:145]
	v_mov_b32_e32 v141, v8
	v_lshl_or_b32 v9, s14, 6, v7
	v_lshl_or_b32 v7, v7, 6, v19
	s_lshl_b32 s14, s14, 13
	v_and_b32_e32 v6, 32, v6
	s_lshl_b32 s1, s18, 7
	v_lshl_add_u64 v[12:13], s[70:71], 0, v[140:141]
	v_mov_b32_e32 v147, v8
	v_bitop3_b32 v19, v7, s14, v6 bitop3:0xde
	v_bitop3_b32 v152, v7, s1, v6 bitop3:0xde
	s_add_i32 m0, s11, 0x18000
	v_lshl_add_u64 v[6:7], v[10:11], 0, s[94:95]
	v_lshl_add_u64 v[14:15], s[78:79], 0, v[146:147]
	v_mov_b32_e32 v143, v8
	s_waitcnt vmcnt(4)
	s_barrier
	global_load_lds_dwordx4 v[6:7], off
	v_lshl_add_u64 v[6:7], v[12:13], 0, s[94:95]
	s_add_i32 m0, s11, 0x1a000
	s_add_i32 s14, s11, 0x8000
	s_add_i32 s15, s11, 0xa000
	v_lshl_add_u64 v[16:17], s[78:79], 0, v[142:143]
	global_load_lds_dwordx4 v[6:7], off
	v_lshl_add_u64 v[6:7], v[14:15], 0, s[94:95]
	s_mov_b32 m0, s14
	s_add_u32 s16, s70, 0x40080
	global_load_lds_dwordx4 v[6:7], off
	v_lshl_add_u64 v[6:7], v[16:17], 0, s[94:95]
	s_mov_b32 m0, s15
	s_addc_u32 s17, s71, 0
	global_load_lds_dwordx4 v[6:7], off
	s_add_i32 m0, s11, 0x1c000
	v_lshl_add_u64 v[6:7], s[16:17], 0, v[144:145]
	global_load_lds_dwordx4 v[6:7], off
	v_lshl_add_u64 v[6:7], s[16:17], 0, v[140:141]
	s_add_i32 m0, s11, 0x1e000
	s_mov_b32 s1, s3
	global_load_lds_dwordx4 v[6:7], off
	v_lshlrev_b32_e32 v6, 14, v4
	v_and_b32_e32 v6, 0xffff8000, v6
	v_lshl_add_u32 v3, v3, 11, v6
	v_and_b32_e32 v4, 1, v4
	v_lshl_or_b32 v3, v4, 6, v3
	v_lshl_add_u32 v148, v5, 1, v3
	v_lshlrev_b32_e32 v3, 14, v0
	v_and_b32_e32 v3, 0xffff8000, v3
	s_waitcnt vmcnt(6)
	v_lshl_add_u32 v1, v1, 11, v3
	v_and_b32_e32 v0, 1, v0
	v_lshl_or_b32 v0, v0, 6, v1
	v_or_b32_e32 v153, s18, v18
	v_mov_b32_e32 v149, v8
	v_lshl_add_u32 v150, v2, 1, v0
	v_mov_b32_e32 v151, v8
	s_mov_b32 s43, 0
	v_add_u32_e32 v154, 16, v19
	s_barrier
	s_cmp_lg_u32 s46, 0x100
	s_cbranch_scc1 .Lds643_x
	s_and_b32 s99, s0, 0xff
	s_cmp_eq_u32 s99, 0
	s_cbranch_scc1 .Lds643_x
	s_cmp_lt_u32 s92, s99
	s_cbranch_scc1 .Lds643_x
	s_sub_u32 s98, s92, s99
	s_mul_i32 s98, s98, 26
	s_lshr_b32 s98, s98, 8
	s_add_u32 s98, s98, 9
	s_min_u32 s98, s98, 20

; #define PG8_STAGE(bufoff, gbase, voff) do { _Pragma("unroll") for (int _i = 0; _i < 2; ++_i) \
;         __builtin_amdgcn_global_load_lds((const unsigned*)((const char*)(gbase) + (voff)[_i]), (LAS unsigned*)(lds + (bufoff) + ldsw + _i * 8192), 16, 0, 0); } while (0)
; #define PG8_WAIT_V(n) asm volatile("s_waitcnt vmcnt(" #n ")" ::: "memory")
; #define PG8_BAR __builtin_amdgcn_s_barrier()
; template <class Epi, class Sched>
; __device__ __forceinline__ void gemm_phase(LAS unsigned char* lds, const Gemm g, const Sched& S, const Epi& E) {
;     ...
;     const unsigned ldsw = (unsigned)wid * 1024u;
;     const int aoff = lds_byte(wr * 64 + fr, fq * 8), boff = lds_byte(wc * 32 + fr, fq * 8);
;     ...
;     PG8_STAGE(PG8_SB(0, 0), cB, voffB); PG8_STAGE(PG8_SA(0, 0), cA, voffA); PG8_STAGE(PG8_SB(0, 1), cB + hstep, voffB); PG8_STAGE(PG8_SA(0, 1), cA + hstep, voffA);
;     if (wr == 1) PG8_BAR;
;     PG8_WAIT_V(4); PG8_BAR;
;     PG8_STAGE(PG8_SB(1, 0), cB + kstep, voffB); PG8_STAGE(PG8_SA(1, 0), cA + kstep, voffA); PG8_STAGE(PG8_SB(1, 1), cB + hstep + kstep, voffB);
;     PG8_WAIT_V(6); PG8_BAR;
.LBB0_817:
	v_lshrrev_b32_e32 v20, 1, v18
	v_and_b32_e32 v20, 24, v20
	s_lshl_b32 s0, s0, 5
	v_and_b32_e32 v19, 15, v18
	v_lshlrev_b32_e32 v21, 1, v20
	v_lshlrev_b32_e32 v18, 2, v18
	s_and_b32 s16, s0, 0x60
	s_add_i32 m0, s11, 0x18000
	v_lshl_add_u64 v[6:7], v[6:7], 0, s[94:95]
	v_lshl_or_b32 v9, s1, 6, v19
	v_lshl_or_b32 v19, v19, 6, v21
	s_lshl_b32 s1, s1, 13
	v_and_b32_e32 v18, 32, v18
	s_lshl_b32 s0, s16, 7
	s_waitcnt vmcnt(4)
	s_barrier
	global_load_lds_dwordx4 v[6:7], off
	v_lshl_add_u64 v[4:5], v[4:5], 0, s[94:95]
	s_add_i32 m0, s11, 0x1a000
	s_add_i32 s14, s11, 0x8000
	s_add_i32 s15, s11, 0xa000
	v_bitop3_b32 v152, v19, s0, v18 bitop3:0xde
	global_load_lds_dwordx4 v[4:5], off
	v_lshl_add_u64 v[2:3], v[2:3], 0, s[94:95]
	s_mov_b32 m0, s14
	s_add_u32 s0, s72, 0xb0080
	v_bitop3_b32 v21, v19, s1, v18 bitop3:0xde
	global_load_lds_dwordx4 v[2:3], off
	v_lshl_add_u64 v[0:1], v[0:1], 0, s[94:95]
	s_mov_b32 m0, s15
	s_addc_u32 s1, s73, 0
	global_load_lds_dwordx4 v[0:1], off
	s_add_i32 m0, s11, 0x1c000
	v_lshl_add_u64 v[0:1], s[0:1], 0, v[144:145]
	global_load_lds_dwordx4 v[0:1], off
	v_lshl_add_u64 v[0:1], s[0:1], 0, v[140:141]
	s_add_i32 m0, s11, 0x1e000
	v_or_b32_e32 v153, s16, v20
	global_load_lds_dwordx4 v[0:1], off
	v_lshrrev_b32_e32 v1, 1, v15
	v_mul_lo_u32 v0, v14, s20
	s_mov_b32 s16, 0xb000
	v_mad_u64_u32 v[0:1], s[0:1], v1, s16, v[0:1]
	v_or_b32_e32 v0, v0, v16
	v_add_lshl_u32 v0, v0, v17, 1
	v_mov_b32_e32 v1, v8
	s_mov_b64 s[18:19], 0xb0080
	v_lshl_add_u64 v[148:149], v[0:1], 0, s[18:19]
	v_lshrrev_b32_e32 v1, 1, v10
	v_mul_lo_u32 v0, v11, s20
	v_mad_u64_u32 v[0:1], s[0:1], v1, s16, v[0:1]
	s_waitcnt vmcnt(6)
	v_or_b32_e32 v0, v0, v12
	v_add_lshl_u32 v0, v0, v13, 1
	v_mov_b32_e32 v1, v8
	v_lshl_add_u64 v[150:151], v[0:1], 0, s[18:19]
	s_mov_b32 s79, 0
	v_add_u32_e32 v154, 16, v21
	s_barrier
	s_cmp_lg_u32 s46, 0x100
	s_cbranch_scc1 .Lds818_x
	s_and_b32 s99, s2, 0xff
	s_cmp_eq_u32 s99, 0
	s_cbranch_scc1 .Lds818_x
	s_cmp_lt_u32 s92, s99
	s_cbranch_scc1 .Lds818_x
	s_mov_b32 s98, 10
	s_min_u32 s98, s98, 20
